# P + hand-generated EpiSwiglu epilogue (all row-stat loads first, batched lane sums) with packed f32 mul/fma for the non-transcendental part
# baseline (speedup 1.0000x reference)
; __device__ __forceinline__ float row_ms(const float* ssq, int row, int fq) {
;     const f32x4 a = *(const f32x4*)(ssq + (size_t)row * 32 + fq * 8), b = *(const f32x4*)(ssq + (size_t)row * 32 + fq * 8 + 4);
;     float s = ((a[0] + a[1]) + (a[2] + a[3])) + ((b[0] + b[1]) + (b[2] + b[3]));
;     s += __shfl_xor(s, 16); s += __shfl_xor(s, 32);
;     return s * (1.0f / 2048.0f) + 1e-6f;
; }
;     __device__ __forceinline__ void operator()(const f32x4 (&acc)[2][2][4][2], const Unit& u, int wr, int wc, int fr, int fq) const {
;         const int row0 = u.pm * BM + wr * 64 + fr, col0 = u.pn * HALF + wc * 32 + 8 * fq;
; #pragma unroll
;         for (int ai = 0; ai < 2; ++ai)
; #pragma unroll
;             for (int m = 0; m < 4; ++m) { const int row = row0 + ai * HALF + m * 16; const float ms = row_ms(ssq, row, fq);
.Lpeel_exit_331:
	v_lshl_add_u32 v140, s58, 8, v142
	v_mov_b32_e32 v141, 0
	v_cmp_lt_i32_e32 vcc, v179, v180
	v_lshlrev_b32_e32 v146, 7, v140
	v_mov_b32_e32 v147, 0
	v_cndmask_b32_e32 v155, v178, v179, vcc
	v_cmp_lt_i32_e32 vcc, v187, v180
	v_lshl_add_u64 v[148:149], v[146:147], 0, v[134:135]
	v_mov_b32_e32 v190, 0x1000
	v_cndmask_b32_e32 v247, v178, v187, vcc
	v_mov_b32_e32 v191, 0
	v_lshlrev_b32_e32 v155, 2, v155
	v_lshlrev_b32_e32 v247, 2, v247
	v_lshl_add_u64 v[150:151], v[148:149], 0, v[190:191]
	v_mov_b32_e32 v190, 0x4000
	global_load_dwordx4 v[192:195], v[148:149], off
	global_load_dwordx4 v[196:199], v[148:149], off offset:16
	global_load_dwordx4 v[200:203], v[148:149], off offset:2048
	global_load_dwordx4 v[204:207], v[148:149], off offset:2064
	v_lshl_add_u64 v[182:183], v[148:149], 0, v[190:191]
	global_load_dwordx4 v[208:211], v[150:151], off
	global_load_dwordx4 v[212:215], v[150:151], off offset:16
	global_load_dwordx4 v[216:219], v[150:151], off offset:2048
	global_load_dwordx4 v[220:223], v[150:151], off offset:2064
	v_lshl_add_u64 v[184:185], v[150:151], 0, v[190:191]
	global_load_dwordx4 v[224:227], v[182:183], off
	global_load_dwordx4 v[228:231], v[182:183], off offset:16
	global_load_dwordx4 v[232:235], v[182:183], off offset:2048
	global_load_dwordx4 v[156:159], v[182:183], off offset:2064
	global_load_dwordx4 v[160:163], v[184:185], off
	global_load_dwordx4 v[164:167], v[184:185], off offset:16
	global_load_dwordx4 v[168:171], v[184:185], off offset:2048
	global_load_dwordx4 v[172:175], v[184:185], off offset:2064
	v_mov_b64_e32 v[190:191], s[38:39]
	v_lshl_or_b32 v250, s55, 7, v144
	v_mov_b32_e32 v251, 0
	v_mad_i64_i32 v[188:189], s[58:59], v140, s4, v[190:191]
	v_lshlrev_b32_e32 v250, 1, v250
	v_mov_b32_e32 v248, 0x2c000
	v_mov_b32_e32 v249, 0
	v_lshl_add_u64 v[188:189], v[188:189], 0, v[250:251]
	v_mov_b32_e32 v250, 0xdc000
	s_and_b64 vcc, exec, s[36:37]
	s_cbranch_vccz .LBB0_334
	s_barrier
.LBB0_334:
	s_waitcnt vmcnt(14)
	v_add_f32_e32 v192, v192, v193
	v_add_f32_e32 v194, v194, v195
	v_add_f32_e32 v196, v196, v197
	v_add_f32_e32 v198, v198, v199
	v_add_f32_e32 v192, v192, v194
	v_add_f32_e32 v196, v196, v198
	v_add_f32_e32 v239, v192, v196
	ds_bpermute_b32 v192, v155, v239
	s_waitcnt vmcnt(12)
	v_add_f32_e32 v200, v200, v201
	v_add_f32_e32 v202, v202, v203
	v_add_f32_e32 v204, v204, v205
	v_add_f32_e32 v206, v206, v207
	v_add_f32_e32 v200, v200, v202
	v_add_f32_e32 v204, v204, v206
	v_add_f32_e32 v240, v200, v204
	ds_bpermute_b32 v193, v155, v240
	s_waitcnt vmcnt(10)
	v_add_f32_e32 v208, v208, v209
	v_add_f32_e32 v210, v210, v211
	v_add_f32_e32 v212, v212, v213
	v_add_f32_e32 v214, v214, v215
	v_add_f32_e32 v208, v208, v210
	v_add_f32_e32 v212, v212, v214
	v_add_f32_e32 v241, v208, v212
	ds_bpermute_b32 v194, v155, v241
	s_waitcnt vmcnt(8)
	v_add_f32_e32 v216, v216, v217
	v_add_f32_e32 v218, v218, v219
	v_add_f32_e32 v220, v220, v221
	v_add_f32_e32 v222, v222, v223
	v_add_f32_e32 v216, v216, v218
	v_add_f32_e32 v220, v220, v222
	v_add_f32_e32 v242, v216, v220
	ds_bpermute_b32 v195, v155, v242
	s_waitcnt vmcnt(6)
	v_add_f32_e32 v224, v224, v225
	v_add_f32_e32 v226, v226, v227
	v_add_f32_e32 v228, v228, v229
	v_add_f32_e32 v230, v230, v231
	v_add_f32_e32 v224, v224, v226
	v_add_f32_e32 v228, v228, v230
	v_add_f32_e32 v243, v224, v228
	ds_bpermute_b32 v196, v155, v243
	s_waitcnt vmcnt(4)
	v_add_f32_e32 v232, v232, v233
	v_add_f32_e32 v234, v234, v235
	v_add_f32_e32 v156, v156, v157
	v_add_f32_e32 v158, v158, v159
	v_add_f32_e32 v232, v232, v234
	v_add_f32_e32 v156, v156, v158
	v_add_f32_e32 v244, v232, v156
	ds_bpermute_b32 v197, v155, v244
	s_waitcnt vmcnt(2)
	v_add_f32_e32 v160, v160, v161
	v_add_f32_e32 v162, v162, v163
	v_add_f32_e32 v164, v164, v165
	v_add_f32_e32 v166, v166, v167
	v_add_f32_e32 v160, v160, v162
	v_add_f32_e32 v164, v164, v166
	v_add_f32_e32 v245, v160, v164
	ds_bpermute_b32 v198, v155, v245
	s_waitcnt vmcnt(0)
	v_add_f32_e32 v168, v168, v169
	v_add_f32_e32 v170, v170, v171
	v_add_f32_e32 v172, v172, v173
	v_add_f32_e32 v174, v174, v175
	v_add_f32_e32 v168, v168, v170
	v_add_f32_e32 v172, v172, v174
	v_add_f32_e32 v246, v168, v172
	ds_bpermute_b32 v199, v155, v246
	s_waitcnt lgkmcnt(7)
	v_add_f32_e32 v239, v239, v192
	ds_bpermute_b32 v192, v247, v239
	s_waitcnt lgkmcnt(7)
	v_add_f32_e32 v240, v240, v193
	ds_bpermute_b32 v193, v247, v240
	s_waitcnt lgkmcnt(7)
	v_add_f32_e32 v241, v241, v194
	ds_bpermute_b32 v194, v247, v241
	s_waitcnt lgkmcnt(7)
	v_add_f32_e32 v242, v242, v195
	ds_bpermute_b32 v195, v247, v242
	s_waitcnt lgkmcnt(7)
	v_add_f32_e32 v243, v243, v196
	ds_bpermute_b32 v196, v247, v243
	s_waitcnt lgkmcnt(7)
	v_add_f32_e32 v244, v244, v197
	ds_bpermute_b32 v197, v247, v244
	s_waitcnt lgkmcnt(7)
	v_add_f32_e32 v245, v245, v198
	ds_bpermute_b32 v198, v247, v245
	s_waitcnt lgkmcnt(7)
	v_add_f32_e32 v246, v246, v199
	ds_bpermute_b32 v199, v247, v246
	s_waitcnt lgkmcnt(7)
	v_add_f32_e32 v239, v239, v192
	s_waitcnt lgkmcnt(6)
	v_add_f32_e32 v240, v240, v193
	s_waitcnt lgkmcnt(5)
	v_add_f32_e32 v241, v241, v194
	s_waitcnt lgkmcnt(4)
	v_add_f32_e32 v242, v242, v195
	s_waitcnt lgkmcnt(3)
	v_add_f32_e32 v243, v243, v196
	s_waitcnt lgkmcnt(2)
	v_add_f32_e32 v244, v244, v197
	s_waitcnt lgkmcnt(1)
	v_add_f32_e32 v245, v245, v198
	s_waitcnt lgkmcnt(0)
; __device__ __forceinline__ unsigned cvt_pk_bf16(float lo, float hi) { unsigned r; asm volatile("v_cvt_pk_bf16_f32 %0, %1, %2" : "=v"(r) : "v"(lo), "v"(hi)); return r; }
;     __device__ __forceinline__ void operator()(const f32x4 (&acc)[2][2][4][2], const Unit& u, int wr, int wc, int fr, int fq) const {
;     ...
;             for (int m = 0; m < 4; ++m) { const int row = row0 + ai * HALF + m * 16; const float ms = row_ms(ssq, row, fq);
;                 const float cexp = -1.4426950408889634f * __builtin_amdgcn_rsqf(ms);
;                 float v[8];
; #pragma unroll
;                 for (int n = 0; n < 2; ++n)
; #pragma unroll
;                     for (int i = 0; i < 4; ++i) { const float a = acc[ai][0][m][n][i], b = acc[ai][1][m][n][i];
;                         v[n * 4 + i] = (a * b) * __builtin_amdgcn_rcpf(__builtin_fmaf(__builtin_amdgcn_exp2f(a * cexp), ms, ms)); }
;                 u32x4 w; w.x = cvt_pk_bf16(v[0], v[1]); w.y = cvt_pk_bf16(v[2], v[3]); w.z = cvt_pk_bf16(v[4], v[5]); w.w = cvt_pk_bf16(v[6], v[7]);
;                 *(u32x4*)(O + (size_t)row * ldc + col0) = w; }
	v_add_f32_e32 v246, v246, v199
	v_fmamk_f32 v239, v239, 0x3a000000, v177
	v_fmamk_f32 v240, v240, 0x3a000000, v177
	v_fmamk_f32 v241, v241, 0x3a000000, v177
	v_fmamk_f32 v242, v242, 0x3a000000, v177
	v_fmamk_f32 v243, v243, 0x3a000000, v177
	v_fmamk_f32 v244, v244, 0x3a000000, v177
	v_fmamk_f32 v245, v245, 0x3a000000, v177
	v_fmamk_f32 v246, v246, 0x3a000000, v177
	v_rsq_f32_e32 v192, v239
	v_rsq_f32_e32 v193, v240
	v_rsq_f32_e32 v194, v241
	v_rsq_f32_e32 v195, v242
	v_rsq_f32_e32 v196, v243
	v_rsq_f32_e32 v197, v244
	v_rsq_f32_e32 v198, v245
	v_rsq_f32_e32 v199, v246
	s_nop 0
	v_mul_f32_e32 v192, 0xbfb8aa3b, v192
	v_mul_f32_e32 v193, 0xbfb8aa3b, v193
	v_mul_f32_e32 v194, 0xbfb8aa3b, v194
	v_mul_f32_e32 v195, 0xbfb8aa3b, v195
	v_mul_f32_e32 v196, 0xbfb8aa3b, v196
	v_mul_f32_e32 v197, 0xbfb8aa3b, v197
	v_mul_f32_e32 v198, 0xbfb8aa3b, v198
	v_mul_f32_e32 v199, 0xbfb8aa3b, v199
	v_pk_mul_f32 v[124:125], v[116:117], v[124:125]
	v_pk_mul_f32 v[126:127], v[118:119], v[126:127]
	v_pk_mul_f32 v[120:121], v[112:113], v[120:121]
	v_pk_mul_f32 v[122:123], v[114:115], v[122:123]
	v_pk_mul_f32 v[116:117], v[116:117], v[192:193] op_sel:[0,0] op_sel_hi:[1,0]
	v_pk_mul_f32 v[118:119], v[118:119], v[192:193] op_sel:[0,0] op_sel_hi:[1,0]
	v_pk_mul_f32 v[112:113], v[112:113], v[192:193] op_sel:[0,0] op_sel_hi:[1,0]
	v_pk_mul_f32 v[114:115], v[114:115], v[192:193] op_sel:[0,0] op_sel_hi:[1,0]
	v_exp_f32_e32 v116, v116
	v_exp_f32_e32 v117, v117
	v_exp_f32_e32 v118, v118
	v_exp_f32_e32 v119, v119
	v_exp_f32_e32 v112, v112
	v_exp_f32_e32 v113, v113
	v_exp_f32_e32 v114, v114
	v_exp_f32_e32 v115, v115
	v_pk_fma_f32 v[116:117], v[116:117], v[238:239], v[238:239] op_sel:[0,1,1] op_sel_hi:[1,1,1]
	v_pk_fma_f32 v[118:119], v[118:119], v[238:239], v[238:239] op_sel:[0,1,1] op_sel_hi:[1,1,1]
	v_pk_fma_f32 v[112:113], v[112:113], v[238:239], v[238:239] op_sel:[0,1,1] op_sel_hi:[1,1,1]
	v_pk_fma_f32 v[114:115], v[114:115], v[238:239], v[238:239] op_sel:[0,1,1] op_sel_hi:[1,1,1]
	v_rcp_f32_e32 v116, v116
	v_rcp_f32_e32 v117, v117
	v_rcp_f32_e32 v118, v118
	v_rcp_f32_e32 v119, v119
	v_rcp_f32_e32 v112, v112
	v_rcp_f32_e32 v113, v113
	v_rcp_f32_e32 v114, v114
	v_rcp_f32_e32 v115, v115
	s_nop 0
	v_pk_mul_f32 v[124:125], v[124:125], v[116:117]
	v_pk_mul_f32 v[126:127], v[126:127], v[118:119]
	v_pk_mul_f32 v[120:121], v[120:121], v[112:113]
	v_pk_mul_f32 v[122:123], v[122:123], v[114:115]
	v_cvt_pk_bf16_f32 v116, v124, v125
	v_cvt_pk_bf16_f32 v117, v126, v127
	v_cvt_pk_bf16_f32 v118, v120, v121
	v_cvt_pk_bf16_f32 v119, v122, v123
	global_store_dwordx4 v[188:189], v[116:119], off
	v_lshl_add_u64 v[188:189], v[188:189], 0, v[248:249]
	v_pk_mul_f32 v[108:109], v[104:105], v[108:109]
	v_pk_mul_f32 v[110:111], v[106:107], v[110:111]
	v_pk_mul_f32 v[100:101], v[96:97], v[100:101]
	v_pk_mul_f32 v[102:103], v[98:99], v[102:103]
	v_pk_mul_f32 v[104:105], v[104:105], v[192:193] op_sel:[0,1] op_sel_hi:[1,1]
	v_pk_mul_f32 v[106:107], v[106:107], v[192:193] op_sel:[0,1] op_sel_hi:[1,1]
	v_pk_mul_f32 v[96:97], v[96:97], v[192:193] op_sel:[0,1] op_sel_hi:[1,1]
	v_pk_mul_f32 v[98:99], v[98:99], v[192:193] op_sel:[0,1] op_sel_hi:[1,1]
	v_exp_f32_e32 v104, v104
	v_exp_f32_e32 v105, v105
	v_exp_f32_e32 v106, v106
	v_exp_f32_e32 v107, v107
	v_exp_f32_e32 v96, v96
	v_exp_f32_e32 v97, v97
	v_exp_f32_e32 v98, v98
	v_exp_f32_e32 v99, v99
	v_pk_fma_f32 v[104:105], v[104:105], v[240:241], v[240:241] op_sel:[0,0,0] op_sel_hi:[1,0,0]
	v_pk_fma_f32 v[106:107], v[106:107], v[240:241], v[240:241] op_sel:[0,0,0] op_sel_hi:[1,0,0]
	v_pk_fma_f32 v[96:97], v[96:97], v[240:241], v[240:241] op_sel:[0,0,0] op_sel_hi:[1,0,0]
	v_pk_fma_f32 v[98:99], v[98:99], v[240:241], v[240:241] op_sel:[0,0,0] op_sel_hi:[1,0,0]
	v_rcp_f32_e32 v104, v104
	v_rcp_f32_e32 v105, v105
	v_rcp_f32_e32 v106, v106
	v_rcp_f32_e32 v107, v107
	v_rcp_f32_e32 v96, v96
	v_rcp_f32_e32 v97, v97
	v_rcp_f32_e32 v98, v98
	v_rcp_f32_e32 v99, v99
	s_nop 0
	v_pk_mul_f32 v[108:109], v[108:109], v[104:105]
	v_pk_mul_f32 v[110:111], v[110:111], v[106:107]
	v_pk_mul_f32 v[100:101], v[100:101], v[96:97]
	v_pk_mul_f32 v[102:103], v[102:103], v[98:99]
	v_cvt_pk_bf16_f32 v104, v108, v109
	v_cvt_pk_bf16_f32 v105, v110, v111
	v_cvt_pk_bf16_f32 v106, v100, v101
	v_cvt_pk_bf16_f32 v107, v102, v103
	global_store_dwordx4 v[188:189], v[104:107], off
	v_lshl_add_u64 v[188:189], v[188:189], 0, v[248:249]
	v_pk_mul_f32 v[92:93], v[88:89], v[92:93]
	v_pk_mul_f32 v[94:95], v[90:91], v[94:95]
	v_pk_mul_f32 v[84:85], v[80:81], v[84:85]
	v_pk_mul_f32 v[86:87], v[82:83], v[86:87]
	v_pk_mul_f32 v[88:89], v[88:89], v[194:195] op_sel:[0,0] op_sel_hi:[1,0]
	v_pk_mul_f32 v[90:91], v[90:91], v[194:195] op_sel:[0,0] op_sel_hi:[1,0]
	v_pk_mul_f32 v[80:81], v[80:81], v[194:195] op_sel:[0,0] op_sel_hi:[1,0]
	v_pk_mul_f32 v[82:83], v[82:83], v[194:195] op_sel:[0,0] op_sel_hi:[1,0]
	v_exp_f32_e32 v88, v88
	v_exp_f32_e32 v89, v89
	v_exp_f32_e32 v90, v90
	v_exp_f32_e32 v91, v91
	v_exp_f32_e32 v80, v80
	v_exp_f32_e32 v81, v81
	v_exp_f32_e32 v82, v82
	v_exp_f32_e32 v83, v83
	v_pk_fma_f32 v[88:89], v[88:89], v[240:241], v[240:241] op_sel:[0,1,1] op_sel_hi:[1,1,1]
	v_pk_fma_f32 v[90:91], v[90:91], v[240:241], v[240:241] op_sel:[0,1,1] op_sel_hi:[1,1,1]
	v_pk_fma_f32 v[80:81], v[80:81], v[240:241], v[240:241] op_sel:[0,1,1] op_sel_hi:[1,1,1]
	v_pk_fma_f32 v[82:83], v[82:83], v[240:241], v[240:241] op_sel:[0,1,1] op_sel_hi:[1,1,1]
	v_rcp_f32_e32 v88, v88
	v_rcp_f32_e32 v89, v89
	v_rcp_f32_e32 v90, v90
	v_rcp_f32_e32 v91, v91
	v_rcp_f32_e32 v80, v80
	v_rcp_f32_e32 v81, v81
	v_rcp_f32_e32 v82, v82
	v_rcp_f32_e32 v83, v83
	s_nop 0
	v_pk_mul_f32 v[92:93], v[92:93], v[88:89]
; __device__ __forceinline__ unsigned cvt_pk_bf16(float lo, float hi) { unsigned r; asm volatile("v_cvt_pk_bf16_f32 %0, %1, %2" : "=v"(r) : "v"(lo), "v"(hi)); return r; }
;     __device__ __forceinline__ void operator()(const f32x4 (&acc)[2][2][4][2], const Unit& u, int wr, int wc, int fr, int fq) const {
;     ...
;             for (int m = 0; m < 4; ++m) { const int row = row0 + ai * HALF + m * 16; const float ms = row_ms(ssq, row, fq);
;                 const float cexp = -1.4426950408889634f * __builtin_amdgcn_rsqf(ms);
;                 float v[8];
; #pragma unroll
;                 for (int n = 0; n < 2; ++n)
; #pragma unroll
;                     for (int i = 0; i < 4; ++i) { const float a = acc[ai][0][m][n][i], b = acc[ai][1][m][n][i];
;                         v[n * 4 + i] = (a * b) * __builtin_amdgcn_rcpf(__builtin_fmaf(__builtin_amdgcn_exp2f(a * cexp), ms, ms)); }
;                 u32x4 w; w.x = cvt_pk_bf16(v[0], v[1]); w.y = cvt_pk_bf16(v[2], v[3]); w.z = cvt_pk_bf16(v[4], v[5]); w.w = cvt_pk_bf16(v[6], v[7]);
;                 *(u32x4*)(O + (size_t)row * ldc + col0) = w; }
	v_pk_mul_f32 v[94:95], v[94:95], v[90:91]
	v_pk_mul_f32 v[84:85], v[84:85], v[80:81]
	v_pk_mul_f32 v[86:87], v[86:87], v[82:83]
	v_cvt_pk_bf16_f32 v88, v92, v93
	v_cvt_pk_bf16_f32 v89, v94, v95
	v_cvt_pk_bf16_f32 v90, v84, v85
	v_cvt_pk_bf16_f32 v91, v86, v87
	global_store_dwordx4 v[188:189], v[88:91], off
	v_lshl_add_u64 v[188:189], v[188:189], 0, v[248:249]
	v_pk_mul_f32 v[76:77], v[72:73], v[76:77]
	v_pk_mul_f32 v[78:79], v[74:75], v[78:79]
	v_pk_mul_f32 v[68:69], v[64:65], v[68:69]
	v_pk_mul_f32 v[70:71], v[66:67], v[70:71]
	v_pk_mul_f32 v[72:73], v[72:73], v[194:195] op_sel:[0,1] op_sel_hi:[1,1]
	v_pk_mul_f32 v[74:75], v[74:75], v[194:195] op_sel:[0,1] op_sel_hi:[1,1]
	v_pk_mul_f32 v[64:65], v[64:65], v[194:195] op_sel:[0,1] op_sel_hi:[1,1]
	v_pk_mul_f32 v[66:67], v[66:67], v[194:195] op_sel:[0,1] op_sel_hi:[1,1]
	v_exp_f32_e32 v72, v72
	v_exp_f32_e32 v73, v73
	v_exp_f32_e32 v74, v74
	v_exp_f32_e32 v75, v75
	v_exp_f32_e32 v64, v64
	v_exp_f32_e32 v65, v65
	v_exp_f32_e32 v66, v66
	v_exp_f32_e32 v67, v67
	v_pk_fma_f32 v[72:73], v[72:73], v[242:243], v[242:243] op_sel:[0,0,0] op_sel_hi:[1,0,0]
	v_pk_fma_f32 v[74:75], v[74:75], v[242:243], v[242:243] op_sel:[0,0,0] op_sel_hi:[1,0,0]
	v_pk_fma_f32 v[64:65], v[64:65], v[242:243], v[242:243] op_sel:[0,0,0] op_sel_hi:[1,0,0]
	v_pk_fma_f32 v[66:67], v[66:67], v[242:243], v[242:243] op_sel:[0,0,0] op_sel_hi:[1,0,0]
	v_rcp_f32_e32 v72, v72
	v_rcp_f32_e32 v73, v73
	v_rcp_f32_e32 v74, v74
	v_rcp_f32_e32 v75, v75
	v_rcp_f32_e32 v64, v64
	v_rcp_f32_e32 v65, v65
	v_rcp_f32_e32 v66, v66
	v_rcp_f32_e32 v67, v67
	s_nop 0
	v_pk_mul_f32 v[76:77], v[76:77], v[72:73]
	v_pk_mul_f32 v[78:79], v[78:79], v[74:75]
	v_pk_mul_f32 v[68:69], v[68:69], v[64:65]
	v_pk_mul_f32 v[70:71], v[70:71], v[66:67]
	v_cvt_pk_bf16_f32 v72, v76, v77
	v_cvt_pk_bf16_f32 v73, v78, v79
	v_cvt_pk_bf16_f32 v74, v68, v69
	v_cvt_pk_bf16_f32 v75, v70, v71
	global_store_dwordx4 v[188:189], v[72:75], off
	v_lshl_add_u64 v[188:189], v[188:189], 0, v[250:251]
	v_pk_mul_f32 v[60:61], v[56:57], v[60:61]
	v_pk_mul_f32 v[62:63], v[58:59], v[62:63]
	v_pk_mul_f32 v[52:53], v[48:49], v[52:53]
	v_pk_mul_f32 v[54:55], v[50:51], v[54:55]
	v_pk_mul_f32 v[56:57], v[56:57], v[196:197] op_sel:[0,0] op_sel_hi:[1,0]
	v_pk_mul_f32 v[58:59], v[58:59], v[196:197] op_sel:[0,0] op_sel_hi:[1,0]
	v_pk_mul_f32 v[48:49], v[48:49], v[196:197] op_sel:[0,0] op_sel_hi:[1,0]
	v_pk_mul_f32 v[50:51], v[50:51], v[196:197] op_sel:[0,0] op_sel_hi:[1,0]
	v_exp_f32_e32 v56, v56
	v_exp_f32_e32 v57, v57
	v_exp_f32_e32 v58, v58
	v_exp_f32_e32 v59, v59
	v_exp_f32_e32 v48, v48
	v_exp_f32_e32 v49, v49
	v_exp_f32_e32 v50, v50
	v_exp_f32_e32 v51, v51
	v_pk_fma_f32 v[56:57], v[56:57], v[242:243], v[242:243] op_sel:[0,1,1] op_sel_hi:[1,1,1]
	v_pk_fma_f32 v[58:59], v[58:59], v[242:243], v[242:243] op_sel:[0,1,1] op_sel_hi:[1,1,1]
	v_pk_fma_f32 v[48:49], v[48:49], v[242:243], v[242:243] op_sel:[0,1,1] op_sel_hi:[1,1,1]
	v_pk_fma_f32 v[50:51], v[50:51], v[242:243], v[242:243] op_sel:[0,1,1] op_sel_hi:[1,1,1]
	v_rcp_f32_e32 v56, v56
	v_rcp_f32_e32 v57, v57
	v_rcp_f32_e32 v58, v58
	v_rcp_f32_e32 v59, v59
	v_rcp_f32_e32 v48, v48
	v_rcp_f32_e32 v49, v49
	v_rcp_f32_e32 v50, v50
	v_rcp_f32_e32 v51, v51
	s_nop 0
	v_pk_mul_f32 v[60:61], v[60:61], v[56:57]
	v_pk_mul_f32 v[62:63], v[62:63], v[58:59]
	v_pk_mul_f32 v[52:53], v[52:53], v[48:49]
	v_pk_mul_f32 v[54:55], v[54:55], v[50:51]
	v_cvt_pk_bf16_f32 v56, v60, v61
	v_cvt_pk_bf16_f32 v57, v62, v63
	v_cvt_pk_bf16_f32 v58, v52, v53
	v_cvt_pk_bf16_f32 v59, v54, v55
	global_store_dwordx4 v[188:189], v[56:59], off
	v_lshl_add_u64 v[188:189], v[188:189], 0, v[248:249]
	v_pk_mul_f32 v[44:45], v[40:41], v[44:45]
	v_pk_mul_f32 v[46:47], v[42:43], v[46:47]
	v_pk_mul_f32 v[36:37], v[32:33], v[36:37]
	v_pk_mul_f32 v[38:39], v[34:35], v[38:39]
	v_pk_mul_f32 v[40:41], v[40:41], v[196:197] op_sel:[0,1] op_sel_hi:[1,1]
	v_pk_mul_f32 v[42:43], v[42:43], v[196:197] op_sel:[0,1] op_sel_hi:[1,1]
	v_pk_mul_f32 v[32:33], v[32:33], v[196:197] op_sel:[0,1] op_sel_hi:[1,1]
	v_pk_mul_f32 v[34:35], v[34:35], v[196:197] op_sel:[0,1] op_sel_hi:[1,1]
	v_exp_f32_e32 v40, v40
	v_exp_f32_e32 v41, v41
	v_exp_f32_e32 v42, v42
	v_exp_f32_e32 v43, v43
	v_exp_f32_e32 v32, v32
	v_exp_f32_e32 v33, v33
	v_exp_f32_e32 v34, v34
	v_exp_f32_e32 v35, v35
; __device__ __forceinline__ unsigned cvt_pk_bf16(float lo, float hi) { unsigned r; asm volatile("v_cvt_pk_bf16_f32 %0, %1, %2" : "=v"(r) : "v"(lo), "v"(hi)); return r; }
; #define PG8_BAR __builtin_amdgcn_s_barrier()
;     __device__ __forceinline__ void operator()(const f32x4 (&acc)[2][2][4][2], const Unit& u, int wr, int wc, int fr, int fq) const {
;     ...
;             for (int m = 0; m < 4; ++m) { const int row = row0 + ai * HALF + m * 16; const float ms = row_ms(ssq, row, fq);
;                 const float cexp = -1.4426950408889634f * __builtin_amdgcn_rsqf(ms);
;                 float v[8];
; #pragma unroll
;                 for (int n = 0; n < 2; ++n)
; #pragma unroll
;                     for (int i = 0; i < 4; ++i) { const float a = acc[ai][0][m][n][i], b = acc[ai][1][m][n][i];
;                         v[n * 4 + i] = (a * b) * __builtin_amdgcn_rcpf(__builtin_fmaf(__builtin_amdgcn_exp2f(a * cexp), ms, ms)); }
;                 u32x4 w; w.x = cvt_pk_bf16(v[0], v[1]); w.y = cvt_pk_bf16(v[2], v[3]); w.z = cvt_pk_bf16(v[4], v[5]); w.w = cvt_pk_bf16(v[6], v[7]);
;                 *(u32x4*)(O + (size_t)row * ldc + col0) = w; }
; template <class Epi, class Sched, bool ALIGN_EPI = false, bool SP2 = false>
; __device__ __forceinline__ void gemm_phase(PG8_LAS unsigned char* lds, const Gemm g, const Sched& S, const Epi& E) {
;     ...
;         if constexpr (!Epi::AFTER_DRAIN) { E(acc, cur, wr, wc, fr, fq); S.done(cur); }
;         if (!has_next) break;
; #pragma unroll
;         for (int a = 0; a < 2; ++a)
; #pragma unroll
;             for (int b = 0; b < 2; ++b)
; #pragma unroll
;                 for (int m = 0; m < 4; ++m)
; #pragma unroll
;                     for (int n = 0; n < 2; ++n) acc[a][b][m][n] = (f32x4){0.f, 0.f, 0.f, 0.f};
;         cur = nxt; cA = nA; cB = nB; ++ui;
;         if constexpr (ALIGN_EPI) { if (wr == 1) PG8_BAR; }
	v_pk_fma_f32 v[40:41], v[40:41], v[244:245], v[244:245] op_sel:[0,0,0] op_sel_hi:[1,0,0]
	v_pk_fma_f32 v[42:43], v[42:43], v[244:245], v[244:245] op_sel:[0,0,0] op_sel_hi:[1,0,0]
	v_pk_fma_f32 v[32:33], v[32:33], v[244:245], v[244:245] op_sel:[0,0,0] op_sel_hi:[1,0,0]
	v_pk_fma_f32 v[34:35], v[34:35], v[244:245], v[244:245] op_sel:[0,0,0] op_sel_hi:[1,0,0]
	v_rcp_f32_e32 v40, v40
	v_rcp_f32_e32 v41, v41
	v_rcp_f32_e32 v42, v42
	v_rcp_f32_e32 v43, v43
	v_rcp_f32_e32 v32, v32
	v_rcp_f32_e32 v33, v33
	v_rcp_f32_e32 v34, v34
	v_rcp_f32_e32 v35, v35
	s_nop 0
	v_pk_mul_f32 v[44:45], v[44:45], v[40:41]
	v_pk_mul_f32 v[46:47], v[46:47], v[42:43]
	v_pk_mul_f32 v[36:37], v[36:37], v[32:33]
	v_pk_mul_f32 v[38:39], v[38:39], v[34:35]
	v_cvt_pk_bf16_f32 v40, v44, v45
	v_cvt_pk_bf16_f32 v41, v46, v47
	v_cvt_pk_bf16_f32 v42, v36, v37
	v_cvt_pk_bf16_f32 v43, v38, v39
	global_store_dwordx4 v[188:189], v[40:43], off
	v_lshl_add_u64 v[188:189], v[188:189], 0, v[248:249]
	v_pk_mul_f32 v[28:29], v[24:25], v[28:29]
	v_pk_mul_f32 v[30:31], v[26:27], v[30:31]
	v_pk_mul_f32 v[20:21], v[16:17], v[20:21]
	v_pk_mul_f32 v[22:23], v[18:19], v[22:23]
	v_pk_mul_f32 v[24:25], v[24:25], v[198:199] op_sel:[0,0] op_sel_hi:[1,0]
	v_pk_mul_f32 v[26:27], v[26:27], v[198:199] op_sel:[0,0] op_sel_hi:[1,0]
	v_pk_mul_f32 v[16:17], v[16:17], v[198:199] op_sel:[0,0] op_sel_hi:[1,0]
	v_pk_mul_f32 v[18:19], v[18:19], v[198:199] op_sel:[0,0] op_sel_hi:[1,0]
	v_exp_f32_e32 v24, v24
	v_exp_f32_e32 v25, v25
	v_exp_f32_e32 v26, v26
	v_exp_f32_e32 v27, v27
	v_exp_f32_e32 v16, v16
	v_exp_f32_e32 v17, v17
	v_exp_f32_e32 v18, v18
	v_exp_f32_e32 v19, v19
	v_pk_fma_f32 v[24:25], v[24:25], v[244:245], v[244:245] op_sel:[0,1,1] op_sel_hi:[1,1,1]
	v_pk_fma_f32 v[26:27], v[26:27], v[244:245], v[244:245] op_sel:[0,1,1] op_sel_hi:[1,1,1]
	v_pk_fma_f32 v[16:17], v[16:17], v[244:245], v[244:245] op_sel:[0,1,1] op_sel_hi:[1,1,1]
	v_pk_fma_f32 v[18:19], v[18:19], v[244:245], v[244:245] op_sel:[0,1,1] op_sel_hi:[1,1,1]
	v_rcp_f32_e32 v24, v24
	v_rcp_f32_e32 v25, v25
	v_rcp_f32_e32 v26, v26
	v_rcp_f32_e32 v27, v27
	v_rcp_f32_e32 v16, v16
	v_rcp_f32_e32 v17, v17
	v_rcp_f32_e32 v18, v18
	v_rcp_f32_e32 v19, v19
	s_nop 0
	v_pk_mul_f32 v[28:29], v[28:29], v[24:25]
	v_pk_mul_f32 v[30:31], v[30:31], v[26:27]
	v_pk_mul_f32 v[20:21], v[20:21], v[16:17]
	v_pk_mul_f32 v[22:23], v[22:23], v[18:19]
	v_cvt_pk_bf16_f32 v24, v28, v29
	v_cvt_pk_bf16_f32 v25, v30, v31
	v_cvt_pk_bf16_f32 v26, v20, v21
	v_cvt_pk_bf16_f32 v27, v22, v23
	global_store_dwordx4 v[188:189], v[24:27], off
	v_lshl_add_u64 v[188:189], v[188:189], 0, v[248:249]
	v_pk_mul_f32 v[12:13], v[8:9], v[12:13]
	v_pk_mul_f32 v[14:15], v[10:11], v[14:15]
	v_pk_mul_f32 v[0:1], v[4:5], v[0:1]
	v_pk_mul_f32 v[2:3], v[6:7], v[2:3]
	v_pk_mul_f32 v[8:9], v[8:9], v[198:199] op_sel:[0,1] op_sel_hi:[1,1]
	v_pk_mul_f32 v[10:11], v[10:11], v[198:199] op_sel:[0,1] op_sel_hi:[1,1]
	v_pk_mul_f32 v[4:5], v[4:5], v[198:199] op_sel:[0,1] op_sel_hi:[1,1]
	v_pk_mul_f32 v[6:7], v[6:7], v[198:199] op_sel:[0,1] op_sel_hi:[1,1]
	v_exp_f32_e32 v8, v8
	v_exp_f32_e32 v9, v9
	v_exp_f32_e32 v10, v10
	v_exp_f32_e32 v11, v11
	v_exp_f32_e32 v4, v4
	v_exp_f32_e32 v5, v5
	v_exp_f32_e32 v6, v6
	v_exp_f32_e32 v7, v7
	v_pk_fma_f32 v[8:9], v[8:9], v[246:247], v[246:247] op_sel:[0,0,0] op_sel_hi:[1,0,0]
	v_pk_fma_f32 v[10:11], v[10:11], v[246:247], v[246:247] op_sel:[0,0,0] op_sel_hi:[1,0,0]
	v_pk_fma_f32 v[4:5], v[4:5], v[246:247], v[246:247] op_sel:[0,0,0] op_sel_hi:[1,0,0]
	v_pk_fma_f32 v[6:7], v[6:7], v[246:247], v[246:247] op_sel:[0,0,0] op_sel_hi:[1,0,0]
	v_rcp_f32_e32 v8, v8
	v_rcp_f32_e32 v9, v9
	v_rcp_f32_e32 v10, v10
	v_rcp_f32_e32 v11, v11
	v_rcp_f32_e32 v4, v4
	v_rcp_f32_e32 v5, v5
	v_rcp_f32_e32 v6, v6
	v_rcp_f32_e32 v7, v7
	s_nop 0
	v_pk_mul_f32 v[12:13], v[12:13], v[8:9]
	v_pk_mul_f32 v[14:15], v[14:15], v[10:11]
	v_pk_mul_f32 v[0:1], v[0:1], v[4:5]
	v_pk_mul_f32 v[2:3], v[2:3], v[6:7]
	v_cvt_pk_bf16_f32 v8, v12, v13
	v_cvt_pk_bf16_f32 v9, v14, v15
	v_cvt_pk_bf16_f32 v10, v0, v1
	v_cvt_pk_bf16_f32 v11, v2, v3
	global_store_dwordx4 v[188:189], v[8:11], off
	s_andn2_b64 vcc, exec, s[40:41]
	s_mov_b64 s[40:41], -1
	s_movk_i32 s81, 0x77e
	s_cbranch_vccnz .LBB0_327
	s_andn2_b64 vcc, exec, s[28:29]
	s_cbranch_vccnz .LBB0_326
	s_barrier
	s_branch .LBB0_326
